# residual GEMM epilogue (G_OUT/FF2) as one contiguous sixteen-block sequence with gate quads loaded once per tile
# baseline (speedup 1.0000x reference)
.LBB0_104:
	s_or_b64 exec, exec, s[60:61]
	s_and_saveexec_b64 s[60:61], s[58:59]
	s_cbranch_execz .LBB0_106
	v_mov_b32_e32 v230, v144
	v_mov_b32_e32 v231, v145
	v_mov_b32_e32 v232, v140
	v_mov_b32_e32 v233, v141
	v_mov_b32_e32 v234, v166
	v_mov_b32_e32 v235, v167
	v_mov_b32_e32 v236, v230
	v_mov_b32_e32 v237, v231
	global_load_dwordx4 v[194:197], v[236:237], off
	global_load_dwordx4 v[198:201], v[236:237], off offset:64
	v_mov_b32_e32 v236, v234
	v_mov_b32_e32 v237, v235
	global_load_dwordx4 v[210:213], v[236:237], off
	global_load_dwordx4 v[214:217], v[236:237], off offset:64
	v_mov_b32_e32 v244, v232
	v_mov_b32_e32 v245, v233
	s_waitcnt vmcnt(0)
	v_pk_fma_f32 v[196:197], v[126:127], v[212:213], v[196:197]
	v_pk_fma_f32 v[194:195], v[124:125], v[210:211], v[194:195]
	global_store_dwordx4 v[244:245], v[194:197], off
	v_pk_fma_f32 v[200:201], v[122:123], v[216:217], v[200:201]
	v_pk_fma_f32 v[198:199], v[120:121], v[214:215], v[198:199]
	global_store_dwordx4 v[244:245], v[198:201], off offset:64
	v_add_co_u32_e32 v236, vcc, 0x200, v230
	v_addc_co_u32_e32 v237, vcc, 0, v231, vcc
	global_load_dwordx4 v[194:197], v[236:237], off
	global_load_dwordx4 v[198:201], v[236:237], off offset:64
	v_add_co_u32_e32 v236, vcc, 0x200, v234
	v_addc_co_u32_e32 v237, vcc, 0, v235, vcc
	global_load_dwordx4 v[218:221], v[236:237], off
	global_load_dwordx4 v[222:225], v[236:237], off offset:64
	v_add_co_u32_e32 v244, vcc, 0x200, v232
	v_addc_co_u32_e32 v245, vcc, 0, v233, vcc
	s_waitcnt vmcnt(0)
	v_pk_fma_f32 v[196:197], v[118:119], v[220:221], v[196:197]
	v_pk_fma_f32 v[194:195], v[116:117], v[218:219], v[194:195]
	global_store_dwordx4 v[244:245], v[194:197], off
	v_pk_fma_f32 v[200:201], v[114:115], v[224:225], v[200:201]
	v_pk_fma_f32 v[198:199], v[112:113], v[222:223], v[198:199]
	global_store_dwordx4 v[244:245], v[198:201], off offset:64
	v_add_co_u32_e32 v236, vcc, 0x10000, v230
	v_addc_co_u32_e32 v237, vcc, 0, v231, vcc
	global_load_dwordx4 v[194:197], v[236:237], off
	global_load_dwordx4 v[198:201], v[236:237], off offset:64
	v_add_co_u32_e32 v244, vcc, 0x10000, v232
	v_addc_co_u32_e32 v245, vcc, 0, v233, vcc
	s_waitcnt vmcnt(0)
	v_pk_fma_f32 v[196:197], v[110:111], v[212:213], v[196:197]
	v_pk_fma_f32 v[194:195], v[108:109], v[210:211], v[194:195]
	global_store_dwordx4 v[244:245], v[194:197], off
	v_pk_fma_f32 v[200:201], v[106:107], v[216:217], v[200:201]
	v_pk_fma_f32 v[198:199], v[104:105], v[214:215], v[198:199]
	global_store_dwordx4 v[244:245], v[198:201], off offset:64
	v_add_co_u32_e32 v236, vcc, 0x10200, v230
	v_addc_co_u32_e32 v237, vcc, 0, v231, vcc
	global_load_dwordx4 v[194:197], v[236:237], off
	global_load_dwordx4 v[198:201], v[236:237], off offset:64
	v_add_co_u32_e32 v244, vcc, 0x10200, v232
	v_addc_co_u32_e32 v245, vcc, 0, v233, vcc
	s_waitcnt vmcnt(0)
	v_pk_fma_f32 v[196:197], v[102:103], v[220:221], v[196:197]
	v_pk_fma_f32 v[194:195], v[100:101], v[218:219], v[194:195]
	global_store_dwordx4 v[244:245], v[194:197], off
	v_pk_fma_f32 v[200:201], v[98:99], v[224:225], v[200:201]
	v_pk_fma_f32 v[198:199], v[96:97], v[222:223], v[198:199]
	global_store_dwordx4 v[244:245], v[198:201], off offset:64
	v_add_co_u32_e32 v236, vcc, 0x20000, v230
	v_addc_co_u32_e32 v237, vcc, 0, v231, vcc
	global_load_dwordx4 v[194:197], v[236:237], off
	global_load_dwordx4 v[198:201], v[236:237], off offset:64
	v_add_co_u32_e32 v244, vcc, 0x20000, v232
	v_addc_co_u32_e32 v245, vcc, 0, v233, vcc
	s_waitcnt vmcnt(0)
	v_pk_fma_f32 v[196:197], v[94:95], v[212:213], v[196:197]
	v_pk_fma_f32 v[194:195], v[92:93], v[210:211], v[194:195]
	global_store_dwordx4 v[244:245], v[194:197], off
	v_pk_fma_f32 v[200:201], v[90:91], v[216:217], v[200:201]
	v_pk_fma_f32 v[198:199], v[88:89], v[214:215], v[198:199]
	global_store_dwordx4 v[244:245], v[198:201], off offset:64
	v_add_co_u32_e32 v236, vcc, 0x20200, v230
	v_addc_co_u32_e32 v237, vcc, 0, v231, vcc
	global_load_dwordx4 v[194:197], v[236:237], off
	global_load_dwordx4 v[198:201], v[236:237], off offset:64
	v_add_co_u32_e32 v244, vcc, 0x20200, v232
	v_addc_co_u32_e32 v245, vcc, 0, v233, vcc
	s_waitcnt vmcnt(0)
	v_pk_fma_f32 v[196:197], v[86:87], v[220:221], v[196:197]
	v_pk_fma_f32 v[194:195], v[84:85], v[218:219], v[194:195]
	global_store_dwordx4 v[244:245], v[194:197], off
	v_pk_fma_f32 v[200:201], v[82:83], v[224:225], v[200:201]
	v_pk_fma_f32 v[198:199], v[80:81], v[222:223], v[198:199]
	global_store_dwordx4 v[244:245], v[198:201], off offset:64
	v_add_co_u32_e32 v236, vcc, 0x30000, v230
	v_addc_co_u32_e32 v237, vcc, 0, v231, vcc
	global_load_dwordx4 v[194:197], v[236:237], off
	global_load_dwordx4 v[198:201], v[236:237], off offset:64
	v_add_co_u32_e32 v244, vcc, 0x30000, v232
	v_addc_co_u32_e32 v245, vcc, 0, v233, vcc
	s_waitcnt vmcnt(0)
	v_pk_fma_f32 v[196:197], v[78:79], v[212:213], v[196:197]
	v_pk_fma_f32 v[194:195], v[76:77], v[210:211], v[194:195]
	global_store_dwordx4 v[244:245], v[194:197], off
	v_pk_fma_f32 v[200:201], v[74:75], v[216:217], v[200:201]
	v_pk_fma_f32 v[198:199], v[72:73], v[214:215], v[198:199]
	global_store_dwordx4 v[244:245], v[198:201], off offset:64
	v_add_co_u32_e32 v236, vcc, 0x30200, v230
	v_addc_co_u32_e32 v237, vcc, 0, v231, vcc
	global_load_dwordx4 v[194:197], v[236:237], off
	global_load_dwordx4 v[198:201], v[236:237], off offset:64
	v_add_co_u32_e32 v244, vcc, 0x30200, v232
	v_addc_co_u32_e32 v245, vcc, 0, v233, vcc
	s_waitcnt vmcnt(0)
	v_pk_fma_f32 v[196:197], v[70:71], v[220:221], v[196:197]
	v_pk_fma_f32 v[194:195], v[68:69], v[218:219], v[194:195]
	global_store_dwordx4 v[244:245], v[194:197], off
	v_pk_fma_f32 v[200:201], v[66:67], v[224:225], v[200:201]
	v_pk_fma_f32 v[198:199], v[64:65], v[222:223], v[198:199]
	global_store_dwordx4 v[244:245], v[198:201], off offset:64
	v_add_co_u32_e32 v236, vcc, 0x80000, v230
	v_addc_co_u32_e32 v237, vcc, 0, v231, vcc
	global_load_dwordx4 v[194:197], v[236:237], off
	global_load_dwordx4 v[198:201], v[236:237], off offset:64
	v_add_co_u32_e32 v244, vcc, 0x80000, v232
	v_addc_co_u32_e32 v245, vcc, 0, v233, vcc
	s_waitcnt vmcnt(0)
	v_pk_fma_f32 v[196:197], v[62:63], v[212:213], v[196:197]
	v_pk_fma_f32 v[194:195], v[60:61], v[210:211], v[194:195]
	global_store_dwordx4 v[244:245], v[194:197], off
	v_pk_fma_f32 v[200:201], v[58:59], v[216:217], v[200:201]
	v_pk_fma_f32 v[198:199], v[56:57], v[214:215], v[198:199]
	global_store_dwordx4 v[244:245], v[198:201], off offset:64
	v_add_co_u32_e32 v236, vcc, 0x80200, v230
	v_addc_co_u32_e32 v237, vcc, 0, v231, vcc
	global_load_dwordx4 v[194:197], v[236:237], off
	global_load_dwordx4 v[198:201], v[236:237], off offset:64
	v_add_co_u32_e32 v244, vcc, 0x80200, v232
	v_addc_co_u32_e32 v245, vcc, 0, v233, vcc
	s_waitcnt vmcnt(0)
	v_pk_fma_f32 v[196:197], v[54:55], v[220:221], v[196:197]
	v_pk_fma_f32 v[194:195], v[52:53], v[218:219], v[194:195]
	global_store_dwordx4 v[244:245], v[194:197], off
	v_pk_fma_f32 v[200:201], v[50:51], v[224:225], v[200:201]
	v_pk_fma_f32 v[198:199], v[48:49], v[222:223], v[198:199]
	global_store_dwordx4 v[244:245], v[198:201], off offset:64
	v_add_co_u32_e32 v236, vcc, 0x90000, v230
	v_addc_co_u32_e32 v237, vcc, 0, v231, vcc
	global_load_dwordx4 v[194:197], v[236:237], off
	global_load_dwordx4 v[198:201], v[236:237], off offset:64
	v_add_co_u32_e32 v244, vcc, 0x90000, v232
	v_addc_co_u32_e32 v245, vcc, 0, v233, vcc
	s_waitcnt vmcnt(0)
	v_pk_fma_f32 v[196:197], v[46:47], v[212:213], v[196:197]
	v_pk_fma_f32 v[194:195], v[44:45], v[210:211], v[194:195]
	global_store_dwordx4 v[244:245], v[194:197], off
	v_pk_fma_f32 v[200:201], v[42:43], v[216:217], v[200:201]
	v_pk_fma_f32 v[198:199], v[40:41], v[214:215], v[198:199]
	global_store_dwordx4 v[244:245], v[198:201], off offset:64
	v_add_co_u32_e32 v236, vcc, 0x90200, v230
	v_addc_co_u32_e32 v237, vcc, 0, v231, vcc
	global_load_dwordx4 v[194:197], v[236:237], off
	global_load_dwordx4 v[198:201], v[236:237], off offset:64
	v_add_co_u32_e32 v244, vcc, 0x90200, v232
	v_addc_co_u32_e32 v245, vcc, 0, v233, vcc
	s_waitcnt vmcnt(0)
	v_pk_fma_f32 v[196:197], v[38:39], v[220:221], v[196:197]
	v_pk_fma_f32 v[194:195], v[36:37], v[218:219], v[194:195]
	global_store_dwordx4 v[244:245], v[194:197], off
	v_pk_fma_f32 v[200:201], v[34:35], v[224:225], v[200:201]
	v_pk_fma_f32 v[198:199], v[32:33], v[222:223], v[198:199]
	global_store_dwordx4 v[244:245], v[198:201], off offset:64
	v_add_co_u32_e32 v236, vcc, 0xa0000, v230
	v_addc_co_u32_e32 v237, vcc, 0, v231, vcc
	global_load_dwordx4 v[194:197], v[236:237], off
	global_load_dwordx4 v[198:201], v[236:237], off offset:64
	v_add_co_u32_e32 v244, vcc, 0xa0000, v232
	v_addc_co_u32_e32 v245, vcc, 0, v233, vcc
	s_waitcnt vmcnt(0)
	v_pk_fma_f32 v[196:197], v[30:31], v[212:213], v[196:197]
	v_pk_fma_f32 v[194:195], v[28:29], v[210:211], v[194:195]
	global_store_dwordx4 v[244:245], v[194:197], off
	v_pk_fma_f32 v[200:201], v[26:27], v[216:217], v[200:201]
	v_pk_fma_f32 v[198:199], v[24:25], v[214:215], v[198:199]
	global_store_dwordx4 v[244:245], v[198:201], off offset:64
	v_add_co_u32_e32 v236, vcc, 0xa0200, v230
	v_addc_co_u32_e32 v237, vcc, 0, v231, vcc
	global_load_dwordx4 v[194:197], v[236:237], off
	global_load_dwordx4 v[198:201], v[236:237], off offset:64
	v_add_co_u32_e32 v244, vcc, 0xa0200, v232
	v_addc_co_u32_e32 v245, vcc, 0, v233, vcc
	s_waitcnt vmcnt(0)
	v_pk_fma_f32 v[196:197], v[22:23], v[220:221], v[196:197]
	v_pk_fma_f32 v[194:195], v[20:21], v[218:219], v[194:195]
	global_store_dwordx4 v[244:245], v[194:197], off
	v_pk_fma_f32 v[200:201], v[18:19], v[224:225], v[200:201]
	v_pk_fma_f32 v[198:199], v[16:17], v[222:223], v[198:199]
	global_store_dwordx4 v[244:245], v[198:201], off offset:64
	v_add_co_u32_e32 v236, vcc, 0xb0000, v230
	v_addc_co_u32_e32 v237, vcc, 0, v231, vcc
	global_load_dwordx4 v[194:197], v[236:237], off
	global_load_dwordx4 v[198:201], v[236:237], off offset:64
	v_add_co_u32_e32 v244, vcc, 0xb0000, v232
	v_addc_co_u32_e32 v245, vcc, 0, v233, vcc
	s_waitcnt vmcnt(0)
	v_pk_fma_f32 v[196:197], v[14:15], v[212:213], v[196:197]
	v_pk_fma_f32 v[194:195], v[12:13], v[210:211], v[194:195]
	global_store_dwordx4 v[244:245], v[194:197], off
	v_pk_fma_f32 v[200:201], v[10:11], v[216:217], v[200:201]
	v_pk_fma_f32 v[198:199], v[8:9], v[214:215], v[198:199]
	global_store_dwordx4 v[244:245], v[198:201], off offset:64
	v_add_co_u32_e32 v236, vcc, 0xb0200, v230
	v_addc_co_u32_e32 v237, vcc, 0, v231, vcc
	global_load_dwordx4 v[194:197], v[236:237], off
	global_load_dwordx4 v[198:201], v[236:237], off offset:64
	v_add_co_u32_e32 v244, vcc, 0xb0200, v232
	v_addc_co_u32_e32 v245, vcc, 0, v233, vcc
	s_waitcnt vmcnt(0)
	v_pk_fma_f32 v[196:197], v[6:7], v[220:221], v[196:197]
	v_pk_fma_f32 v[194:195], v[4:5], v[218:219], v[194:195]
	global_store_dwordx4 v[244:245], v[194:197], off
	v_pk_fma_f32 v[200:201], v[2:3], v[224:225], v[200:201]
	v_pk_fma_f32 v[198:199], v[0:1], v[222:223], v[198:199]
	global_store_dwordx4 v[244:245], v[198:201], off offset:64
	s_or_b64 exec, exec, s[60:61]
	s_movk_i32 s83, 0xff
	s_branch .LBB0_1065
